# sample-unit conv loads of layer 0 (sdn 3 blocks, sssm 2 blocks) issued back to back with one counted wait instead of one round trip per load
# baseline (speedup 1.0000x reference)
.LBB0_593:
	s_lshr_b32 s93, s2, 10
	s_and_b32 s28, s2, 0x3ff
	s_mov_b64 s[2:3], -1
	s_cmp_lt_i32 s93, 2
	s_mov_b64 s[88:89], 0
	s_cbranch_scc1 .LBB0_682
	s_cmp_gt_i32 s93, 2
	s_cbranch_scc0 .LBB0_647
	s_cmp_eq_u32 s93, 3
	s_mov_b64 s[88:89], -1
	s_cbranch_scc0 .LBB0_646
	s_lshl_b32 s10, s28, 3
	v_mov_b32_e32 v72, v89
	s_bitset1_b32 s10, 14
	s_movk_i32 s2, 0x300
	s_mul_i32 s86, s28, 0x2400
	v_readfirstlane_b32 s11, v72
	v_cmp_gt_i32_e32 vcc, s2, v72
	v_ashrrev_i32_e32 v73, 31, v72
	s_mul_i32 s8, s10, 0x1c00
	v_lshl_add_u32 v4, v72, 2, v88
	s_and_saveexec_b64 s[2:3], vcc
	s_cbranch_execz .LBB0_598
	s_load_dwordx2 s[4:5], s[34:35], 0x28
	v_lshlrev_b64 v[0:1], 2, v[72:73]
	v_readlane_b32 s0, v254, 40
	v_readlane_b32 s1, v254, 41
	s_movk_i32 s9, 0x1000
	s_waitcnt lgkmcnt(0)
	v_lshl_add_u64 v[2:3], s[4:5], 0, v[0:1]
	v_lshl_add_u64 v[2:3], v[2:3], 0, s[86:87]
	global_load_dword v13, v[2:3], off
	global_load_dword v12, v[2:3], off offset:3072
	v_add_co_u32_e32 v2, vcc, 0x1000, v2
	s_add_u32 s4, s0, s8
	s_nop 0
	v_addc_co_u32_e32 v3, vcc, 0, v3, vcc
	global_load_dword v11, v[2:3], off offset:2048
	s_addc_u32 s5, s1, 0
	v_lshlrev_b64 v[2:3], 1, v[72:73]
	v_lshl_add_u64 v[6:7], s[4:5], 0, v[2:3]
	s_mul_i32 s4, s28, 0xe000
	s_add_u32 s4, s0, s4
	v_add_co_u32_e32 v6, vcc, s9, v6
	s_addc_u32 s5, s1, 0
	s_nop 0
	v_addc_co_u32_e32 v7, vcc, 0, v7, vcc
	v_lshl_add_u64 v[14:15], s[4:5], 0, v[2:3]
	s_mov_b32 s0, 0x7002000
	v_add_co_u32_e32 v2, vcc, s0, v14
	s_mov_b32 s0, 0x7004000
	s_nop 0
	v_addc_co_u32_e32 v3, vcc, 0, v15, vcc
	global_load_ushort v9, v[2:3], off offset:3072
	s_load_dwordx4 s[4:7], s[34:35], 0x70
	global_load_ushort v10, v[6:7], off
	v_add_co_u32_e32 v2, vcc, s0, v14
	s_mov_b32 s0, 0x7006000
	s_nop 0
	v_addc_co_u32_e32 v3, vcc, 0, v15, vcc
	global_load_ushort v8, v[2:3], off offset:2048
	v_add_co_u32_e32 v2, vcc, s0, v14
	s_mov_b32 s0, 0x7008000
	s_nop 0
	v_addc_co_u32_e32 v3, vcc, 0, v15, vcc
	global_load_ushort v7, v[2:3], off offset:1024
	v_add_co_u32_e32 v2, vcc, s0, v14
	s_mov_b32 s0, 0x7009000
	s_nop 0
	v_addc_co_u32_e32 v3, vcc, 0, v15, vcc
	global_load_ushort v6, v[2:3], off
	v_add_co_u32_e32 v2, vcc, s0, v14
	s_mov_b32 s0, 0x700b000
	s_nop 0
	v_addc_co_u32_e32 v3, vcc, 0, v15, vcc
	v_add_co_u32_e32 v16, vcc, s0, v14
	global_load_ushort v2, v[2:3], off offset:3072
	s_nop 0
	v_addc_co_u32_e32 v17, vcc, 0, v15, vcc
	global_load_ushort v5, v[16:17], off offset:2048
	s_mov_b32 s0, 0x700d000
	v_add_co_u32_e32 v14, vcc, s0, v14
	s_movk_i32 s0, 0x2000
	s_nop 0
	v_addc_co_u32_e32 v15, vcc, 0, v15, vcc
	global_load_ushort v3, v[14:15], off offset:1024
	s_waitcnt lgkmcnt(0)
	v_lshl_add_u64 v[14:15], s[4:5], 0, v[0:1]
	v_add_co_u32_e32 v16, vcc, s9, v14
	global_load_dword v18, v[14:15], off
	global_load_dword v19, v[14:15], off offset:3072
	v_addc_co_u32_e32 v17, vcc, 0, v15, vcc
	v_add_co_u32_e32 v14, vcc, s0, v14
	global_load_dword v16, v[16:17], off offset:2048
	s_nop 0
	v_addc_co_u32_e32 v15, vcc, 0, v15, vcc
	global_load_dword v17, v[14:15], off offset:1024
	v_lshl_add_u64 v[14:15], s[6:7], 0, v[0:1]
	global_load_dword v14, v[14:15], off
	s_load_dwordx4 s[4:7], s[34:35], 0xe0
	s_waitcnt lgkmcnt(0)
	s_add_u32 s4, s4, s86
	s_addc_u32 s5, s5, 0
	v_lshl_add_u64 v[0:1], s[4:5], 0, v[0:1]
	s_waitcnt vmcnt(5)
	v_lshlrev_b32_e32 v9, 16, v9
	v_lshlrev_b32_e32 v10, 16, v10
	v_lshlrev_b32_e32 v8, 16, v8
	v_lshlrev_b32_e32 v7, 16, v7
	v_lshlrev_b32_e32 v6, 16, v6
	v_lshlrev_b32_e32 v2, 16, v2
	v_lshlrev_b32_e32 v5, 16, v5
	v_lshlrev_b32_e32 v3, 16, v3
	s_waitcnt vmcnt(0)
	v_fma_f32 v13, v13, v18, v14
	v_fmac_f32_e32 v13, v12, v19
	v_fmac_f32_e32 v13, v11, v16
	v_fmac_f32_e32 v13, v17, v10
	v_mul_f32_e32 v15, 0xbfb8aa3b, v13
	v_exp_f32_e32 v15, v15
	v_fma_f32 v12, v12, v18, v14
	v_fmac_f32_e32 v12, v11, v19
	v_fmac_f32_e32 v12, v16, v10
	v_add_f32_e32 v15, 1.0, v15
	v_rcp_f32_e32 v15, v15
	v_fmac_f32_e32 v12, v17, v9
	v_fma_f32 v11, v11, v18, v14
	v_fmac_f32_e32 v11, v19, v10
	v_mul_f32_e32 v13, v13, v15
	v_mul_f32_e32 v15, 0xbfb8aa3b, v12
	v_exp_f32_e32 v15, v15
	v_fmac_f32_e32 v11, v16, v9
	v_fmac_f32_e32 v11, v17, v8
	v_fma_f32 v10, v18, v10, v14
	v_add_f32_e32 v15, 1.0, v15
	v_rcp_f32_e32 v15, v15
	v_fmac_f32_e32 v10, v19, v9
	v_fmac_f32_e32 v10, v16, v8
	v_fmac_f32_e32 v10, v17, v7
	v_mul_f32_e32 v12, v12, v15
	ds_write2st64_b32 v4, v13, v12 offset1:12
	v_mul_f32_e32 v12, 0xbfb8aa3b, v11
	v_exp_f32_e32 v12, v12
	v_fma_f32 v9, v18, v9, v14
	v_fmac_f32_e32 v9, v19, v8
	v_fmac_f32_e32 v9, v16, v7
	v_add_f32_e32 v12, 1.0, v12
	v_rcp_f32_e32 v12, v12
	v_fmac_f32_e32 v9, v17, v6
	v_fma_f32 v8, v18, v8, v14
	v_fmac_f32_e32 v8, v19, v7
	v_mul_f32_e32 v11, v11, v12
	v_mul_f32_e32 v12, 0xbfb8aa3b, v10
	v_exp_f32_e32 v12, v12
	v_fmac_f32_e32 v8, v16, v6
	v_fmac_f32_e32 v8, v17, v2
	v_fma_f32 v7, v18, v7, v14
	v_add_f32_e32 v12, 1.0, v12
	v_rcp_f32_e32 v12, v12
	v_fmac_f32_e32 v14, v18, v6
	v_fmac_f32_e32 v7, v19, v6
	v_fmac_f32_e32 v14, v19, v2
	v_mul_f32_e32 v10, v10, v12
	ds_write2st64_b32 v4, v11, v10 offset0:24 offset1:36
	v_mul_f32_e32 v10, 0xbfb8aa3b, v9
	v_exp_f32_e32 v10, v10
	v_fmac_f32_e32 v7, v16, v2
	v_fmac_f32_e32 v14, v16, v5
	v_fmac_f32_e32 v7, v17, v5
	v_add_f32_e32 v10, 1.0, v10
	v_rcp_f32_e32 v10, v10
	v_fmac_f32_e32 v14, v17, v3
	v_mul_f32_e32 v6, 0xbfb8aa3b, v14
	v_exp_f32_e32 v6, v6
	v_mul_f32_e32 v9, v9, v10
	v_mul_f32_e32 v10, 0xbfb8aa3b, v8
	v_exp_f32_e32 v10, v10
	v_add_f32_e32 v6, 1.0, v6
	v_rcp_f32_e32 v6, v6
	v_add_f32_e32 v10, 1.0, v10
	v_rcp_f32_e32 v10, v10
	v_mul_f32_e32 v6, v14, v6
	v_mul_f32_e32 v8, v8, v10
	ds_write2st64_b32 v4, v9, v8 offset0:48 offset1:60
	v_mul_f32_e32 v8, 0xbfb8aa3b, v7
	v_exp_f32_e32 v8, v8
	s_nop 0
	v_add_f32_e32 v8, 1.0, v8
	v_rcp_f32_e32 v8, v8
	s_nop 0
	v_mul_f32_e32 v7, v7, v8
	ds_write2st64_b32 v4, v7, v6 offset0:72 offset1:84
	v_add_co_u32_e32 v6, vcc, 0xaa9b000, v0
	s_nop 1
	v_addc_co_u32_e32 v7, vcc, 0, v1, vcc
	v_add_co_u32_e32 v0, vcc, 0xaa9c000, v0
	global_store_dword v[6:7], v2, off
	global_store_dword v[6:7], v5, off offset:3072
	v_addc_co_u32_e32 v1, vcc, 0, v1, vcc
	global_store_dword v[0:1], v3, off offset:2048
.LBB0_598:
	s_or_b64 exec, exec, s[2:3]
	s_movk_i32 s2, 0x100
	v_cmp_gt_i32_e32 vcc, s2, v72
	s_and_saveexec_b64 s[2:3], vcc
	s_cbranch_execz .LBB0_600
	s_load_dwordx2 s[4:5], s[34:35], 0x28
	v_lshlrev_b64 v[2:3], 2, v[72:73]
	s_mov_b64 s[12:13], 0x800
	v_add_u32_e32 v0, 0x200, v72
	v_readlane_b32 s0, v254, 40
	s_waitcnt lgkmcnt(0)
	v_lshl_add_u64 v[6:7], s[4:5], 0, v[2:3]
	v_lshl_add_u64 v[6:7], v[6:7], 0, s[86:87]
	v_lshl_add_u64 v[8:9], v[6:7], 0, s[12:13]
	global_load_dword v15, v[6:7], off offset:2048
	global_load_dword v14, v[8:9], off offset:3072
	v_add_co_u32_e32 v6, vcc, 0x2000, v6
	v_ashrrev_i32_e32 v1, 31, v0
	s_nop 0
	v_addc_co_u32_e32 v7, vcc, 0, v7, vcc
	v_readlane_b32 s1, v254, 41
	s_add_u32 s4, s0, s8
	global_load_dword v13, v[6:7], off
	s_addc_u32 s5, s1, 0
	v_lshlrev_b64 v[6:7], 1, v[0:1]
	v_lshl_add_u64 v[8:9], s[4:5], 0, v[6:7]
	s_movk_i32 s4, 0x1000
	v_add_co_u32_e32 v8, vcc, s4, v8
	s_mul_i32 s4, s28, 0xe000
	s_nop 0
	v_addc_co_u32_e32 v9, vcc, 0, v9, vcc
	global_load_ushort v12, v[8:9], off
	s_add_u32 s4, s0, s4
	s_addc_u32 s5, s1, 0
	v_lshl_add_u64 v[16:17], s[4:5], 0, v[6:7]
	s_mov_b32 s0, 0x7002000
	v_add_co_u32_e32 v6, vcc, s0, v16
	s_mov_b32 s0, 0x7004000
	s_nop 0
	v_addc_co_u32_e32 v7, vcc, 0, v17, vcc
	s_load_dwordx4 s[4:7], s[34:35], 0x70
	global_load_ushort v11, v[6:7], off offset:3072
	v_add_co_u32_e32 v6, vcc, s0, v16
	s_mov_b32 s0, 0x7006000
	s_nop 0
	v_addc_co_u32_e32 v7, vcc, 0, v17, vcc
	global_load_ushort v10, v[6:7], off offset:2048
	v_add_co_u32_e32 v6, vcc, s0, v16
	s_mov_b32 s0, 0x7008000
	s_nop 0
	v_addc_co_u32_e32 v7, vcc, 0, v17, vcc
	global_load_ushort v9, v[6:7], off offset:1024
	v_add_co_u32_e32 v6, vcc, s0, v16
	s_mov_b32 s0, 0x7009000
	s_nop 0
	v_addc_co_u32_e32 v7, vcc, 0, v17, vcc
	global_load_ushort v8, v[6:7], off
	v_add_co_u32_e32 v6, vcc, s0, v16
	s_mov_b32 s0, 0x700b000
	s_nop 0
	v_addc_co_u32_e32 v7, vcc, 0, v17, vcc
	global_load_ushort v5, v[6:7], off offset:3072
	v_add_co_u32_e32 v6, vcc, s0, v16
	s_mov_b32 s0, 0x700d000
	s_nop 0
	v_addc_co_u32_e32 v7, vcc, 0, v17, vcc
	global_load_ushort v7, v[6:7], off offset:2048
	v_add_co_u32_e32 v16, vcc, s0, v16
	s_movk_i32 s0, 0x2000
	s_nop 0
	v_addc_co_u32_e32 v17, vcc, 0, v17, vcc
	global_load_ushort v6, v[16:17], off offset:1024
	s_waitcnt lgkmcnt(0)
	v_lshl_add_u64 v[16:17], s[4:5], 0, v[2:3]
	v_lshl_add_u64 v[18:19], v[16:17], 0, s[12:13]
	global_load_dword v20, v[16:17], off offset:2048
	s_nop 0
	global_load_dword v18, v[18:19], off offset:3072
	v_add_co_u32_e32 v16, vcc, s0, v16
	v_lshl_add_u64 v[2:3], s[6:7], 0, v[2:3]
	s_nop 0
	v_addc_co_u32_e32 v17, vcc, 0, v17, vcc
	global_load_dword v19, v[16:17], off
	s_nop 0
	global_load_dword v16, v[16:17], off offset:3072
	s_load_dwordx4 s[4:7], s[34:35], 0xe0
	global_load_dword v2, v[2:3], off offset:2048
	s_waitcnt lgkmcnt(0)
	s_add_u32 s4, s4, s86
	s_addc_u32 s5, s5, 0
	v_lshl_add_u64 v[0:1], v[0:1], 2, s[4:5]
	s_waitcnt vmcnt(5)
	v_lshlrev_b32_e32 v12, 16, v12
	v_lshlrev_b32_e32 v11, 16, v11
	v_lshlrev_b32_e32 v10, 16, v10
	v_lshlrev_b32_e32 v9, 16, v9
	v_lshlrev_b32_e32 v8, 16, v8
	v_lshlrev_b32_e32 v5, 16, v5
	v_lshlrev_b32_e32 v7, 16, v7
	v_lshlrev_b32_e32 v6, 16, v6
	s_waitcnt vmcnt(0)
	v_fma_f32 v3, v15, v20, v2
	v_fmac_f32_e32 v3, v14, v18
	v_fmac_f32_e32 v3, v13, v19
	v_fmac_f32_e32 v3, v16, v12
	v_mul_f32_e32 v15, 0xbfb8aa3b, v3
	v_exp_f32_e32 v15, v15
	v_fma_f32 v14, v14, v20, v2
	v_fmac_f32_e32 v14, v13, v18
	v_fmac_f32_e32 v14, v19, v12
	v_add_f32_e32 v15, 1.0, v15
	v_rcp_f32_e32 v15, v15
	v_fmac_f32_e32 v14, v16, v11
	v_mul_f32_e32 v3, v3, v15
	v_mul_f32_e32 v15, 0xbfb8aa3b, v14
	v_exp_f32_e32 v15, v15
	s_nop 0
	v_add_f32_e32 v15, 1.0, v15
	v_rcp_f32_e32 v15, v15
	s_nop 0
	v_mul_f32_e32 v14, v14, v15
	ds_write2st64_b32 v4, v3, v14 offset0:8 offset1:20
	v_fma_f32 v3, v13, v20, v2
	v_fmac_f32_e32 v3, v18, v12
	v_fmac_f32_e32 v3, v19, v11
	v_fmac_f32_e32 v3, v16, v10
	v_mul_f32_e32 v13, 0xbfb8aa3b, v3
	v_exp_f32_e32 v13, v13
	v_fma_f32 v12, v20, v12, v2
	v_fmac_f32_e32 v12, v18, v11
	v_fmac_f32_e32 v12, v19, v10
	v_add_f32_e32 v13, 1.0, v13
	v_rcp_f32_e32 v13, v13
	v_fmac_f32_e32 v12, v16, v9
	v_mul_f32_e32 v3, v3, v13
	v_mul_f32_e32 v13, 0xbfb8aa3b, v12
	v_exp_f32_e32 v13, v13
	s_nop 0
	v_add_f32_e32 v13, 1.0, v13
	v_rcp_f32_e32 v13, v13
	s_nop 0
	v_mul_f32_e32 v12, v12, v13
	ds_write2st64_b32 v4, v3, v12 offset0:32 offset1:44
	v_fma_f32 v3, v20, v11, v2
	v_fmac_f32_e32 v3, v18, v10
	v_fmac_f32_e32 v3, v19, v9
	v_fmac_f32_e32 v3, v16, v8
	v_mul_f32_e32 v11, 0xbfb8aa3b, v3
	v_exp_f32_e32 v11, v11
	v_fma_f32 v10, v20, v10, v2
	v_fmac_f32_e32 v10, v18, v9
	v_fmac_f32_e32 v10, v19, v8
	v_add_f32_e32 v11, 1.0, v11
	v_rcp_f32_e32 v11, v11
	v_fmac_f32_e32 v10, v16, v5
	v_mul_f32_e32 v3, v3, v11
	v_mul_f32_e32 v11, 0xbfb8aa3b, v10
	v_exp_f32_e32 v11, v11
	s_nop 0
	v_add_f32_e32 v11, 1.0, v11
	v_rcp_f32_e32 v11, v11
	s_nop 0
	v_mul_f32_e32 v10, v10, v11
	ds_write2st64_b32 v4, v3, v10 offset0:56 offset1:68
	v_fma_f32 v3, v20, v9, v2
	v_fmac_f32_e32 v2, v20, v8
	v_fmac_f32_e32 v3, v18, v8
	v_fmac_f32_e32 v2, v18, v5
	v_fmac_f32_e32 v3, v19, v5
	v_fmac_f32_e32 v2, v19, v7
	v_fmac_f32_e32 v3, v16, v7
	v_fmac_f32_e32 v2, v16, v6
	v_mul_f32_e32 v9, 0xbfb8aa3b, v3
	v_mul_f32_e32 v8, 0xbfb8aa3b, v2
	v_exp_f32_e32 v9, v9
	v_exp_f32_e32 v8, v8
	v_add_f32_e32 v9, 1.0, v9
	v_add_f32_e32 v8, 1.0, v8
	v_rcp_f32_e32 v9, v9
	v_rcp_f32_e32 v8, v8
	v_mul_f32_e32 v3, v3, v9
	v_mul_f32_e32 v2, v2, v8
	ds_write2st64_b32 v4, v3, v2 offset0:80 offset1:92
	v_add_co_u32_e32 v2, vcc, 0xaa9b000, v0
	s_nop 1
	v_addc_co_u32_e32 v3, vcc, 0, v1, vcc
	v_add_co_u32_e32 v0, vcc, 0xaa9c000, v0
	global_store_dword v[2:3], v5, off
	global_store_dword v[2:3], v7, off offset:3072
	v_addc_co_u32_e32 v1, vcc, 0, v1, vcc
	global_store_dword v[0:1], v6, off offset:2048

.LBB0_732:
	s_and_b64 vcc, exec, s[0:1]
	s_cbranch_vccz .LBB0_573
	v_mov_b32_e32 v150, v89
	s_load_dwordx2 s[0:1], s[34:35], 0x18
	s_load_dwordx2 s[14:15], s[34:35], 0x50
	v_ashrrev_i32_e32 v151, 31, v150
	v_lshlrev_b64 v[0:1], 2, v[150:151]
	s_lshl_b32 s16, s28, 3
	s_waitcnt lgkmcnt(0)
	v_lshl_add_u64 v[2:3], s[0:1], 0, v[0:1]
	v_readlane_b32 s0, v254, 40
	s_bitset1_b32 s16, 14
	v_readlane_b32 s1, v254, 41
	s_mul_i32 s86, s28, 0x4800
	v_lshl_add_u64 v[14:15], v[2:3], 0, s[86:87]
	s_waitcnt vmcnt(0)
	v_lshl_add_u64 v[18:19], v[150:151], 1, s[0:1]
	s_mul_i32 s0, s16, 0x1c00
	s_mov_b32 s1, s87
	v_lshl_add_u64 v[8:9], v[18:19], 0, s[0:1]
	global_load_ushort v25, v[8:9], off
	s_mul_i32 s12, s28, 0xe000
	s_add_i32 s0, s12, 0x7001c00
	s_add_i32 s2, s12, 0x7003800
	s_mov_b32 s3, s87
	s_add_i32 s4, s12, 0x7005400
	s_mov_b32 s5, s87
	s_add_i32 s6, s12, 0x7007000
	s_mov_b32 s7, s87
	s_add_i32 s8, s12, 0x7008c00
	s_mov_b32 s9, s87
	s_add_i32 s10, s12, 0x700a800
	s_mov_b32 s11, s87
	s_add_i32 s12, s12, 0x700c400
	s_mov_b32 s13, s87
	v_add_co_u32_e32 v16, vcc, 0x1000, v14
	v_lshl_add_u64 v[10:11], s[14:15], 0, v[0:1]
	s_nop 0
	v_addc_co_u32_e32 v17, vcc, 0, v15, vcc
	v_add_co_u32_e32 v12, vcc, 0x3000, v14
	s_movk_i32 s14, 0x1000
	s_nop 0
	v_addc_co_u32_e32 v13, vcc, 0, v15, vcc
	v_add_co_u32_e32 v6, vcc, s14, v10
	s_movk_i32 s14, 0x3000
	s_nop 0
	v_addc_co_u32_e32 v7, vcc, 0, v11, vcc
	v_add_co_u32_e32 v20, vcc, s14, v10
	global_load_dword v22, v[14:15], off
	global_load_dword v23, v[16:17], off offset:2048
	global_load_dword v24, v[12:13], off
	v_addc_co_u32_e32 v21, vcc, 0, v11, vcc
	s_movk_i32 s24, 0x4000
	v_add_co_u32_e32 v4, vcc, s24, v10
	v_lshl_add_u32 v30, v150, 2, v88
	s_nop 0
	v_addc_co_u32_e32 v5, vcc, 0, v11, vcc
	v_readfirstlane_b32 s17, v150
	v_lshl_add_u64 v[2:3], v[18:19], 0, s[0:1]
	global_load_ushort v26, v[2:3], off
	v_lshl_add_u64 v[2:3], v[18:19], 0, s[2:3]
	global_load_ushort v27, v[2:3], off
	v_lshl_add_u64 v[2:3], v[18:19], 0, s[4:5]
	global_load_ushort v28, v[2:3], off
	v_lshl_add_u64 v[2:3], v[18:19], 0, s[6:7]
	global_load_ushort v29, v[2:3], off
	v_lshl_add_u64 v[2:3], v[18:19], 0, s[8:9]
	global_load_ushort v39, v[2:3], off
	v_lshl_add_u64 v[2:3], v[18:19], 0, s[10:11]
	global_load_ushort v40, v[2:3], off
	v_lshl_add_u64 v[2:3], v[18:19], 0, s[12:13]
	global_load_ushort v41, v[2:3], off
	global_load_dword v2, v[10:11], off
	global_load_dword v3, v[6:7], off offset:2048
	global_load_dword v31, v[4:5], off offset:-4096
	global_load_dword v42, v[4:5], off offset:2048
	s_waitcnt vmcnt(4)
	v_lshlrev_b32_e32 v25, 16, v25
	v_lshlrev_b32_e32 v26, 16, v26
	v_lshlrev_b32_e32 v27, 16, v27
	v_lshlrev_b32_e32 v28, 16, v28
	v_lshlrev_b32_e32 v29, 16, v29
	v_lshlrev_b32_e32 v39, 16, v39
	v_lshlrev_b32_e32 v40, 16, v40
	v_lshlrev_b32_e32 v41, 16, v41
	s_load_dwordx4 s[20:23], s[34:35], 0xe0
	s_waitcnt lgkmcnt(0)
	s_add_u32 s14, s20, s86
	s_addc_u32 s15, s21, 0
	v_lshl_add_u64 v[0:1], s[14:15], 0, v[0:1]
	s_mov_b64 s[14:15], 0x861b000
	s_movk_i32 s20, 0x2000
	s_waitcnt vmcnt(2)
	v_mul_f32_e32 v32, v23, v3
	v_fmac_f32_e32 v32, v22, v2
	s_waitcnt vmcnt(1)
	v_fmac_f32_e32 v32, v24, v31
	s_waitcnt vmcnt(0)
	v_fmac_f32_e32 v32, v42, v25
	v_mul_f32_e32 v22, 0xbfb8aa3b, v32
	v_exp_f32_e32 v22, v22
	s_nop 0
	v_add_f32_e32 v22, 1.0, v22
	v_rcp_f32_e32 v22, v22
	s_nop 0
	v_mul_f32_e32 v36, v32, v22
	v_mul_f32_e32 v22, v24, v3
	v_fmac_f32_e32 v22, v23, v2
	v_fmac_f32_e32 v22, v31, v25
	v_fmac_f32_e32 v22, v42, v26
	v_mul_f32_e32 v23, 0xbfb8aa3b, v22
	v_exp_f32_e32 v23, v23
	s_nop 0
	v_add_f32_e32 v23, 1.0, v23
	v_rcp_f32_e32 v23, v23
	s_nop 0
	v_mul_f32_e32 v34, v22, v23
	v_mul_f32_e32 v22, v3, v25
	v_fmac_f32_e32 v22, v24, v2
	v_fmac_f32_e32 v22, v31, v26
	v_fmac_f32_e32 v22, v42, v27
	v_mul_f32_e32 v23, 0xbfb8aa3b, v22
	v_exp_f32_e32 v23, v23
	s_nop 0
	v_add_f32_e32 v23, 1.0, v23
	v_rcp_f32_e32 v23, v23
	s_nop 0
	v_mul_f32_e32 v35, v22, v23
	v_mul_f32_e32 v22, v3, v26
	v_fmac_f32_e32 v22, v2, v25
	v_fmac_f32_e32 v22, v31, v27
	v_fmac_f32_e32 v22, v42, v28
	v_mul_f32_e32 v23, 0xbfb8aa3b, v22
	v_exp_f32_e32 v23, v23
	s_nop 0
	v_add_f32_e32 v23, 1.0, v23
	v_rcp_f32_e32 v23, v23
	s_nop 0
	v_mul_f32_e32 v33, v22, v23
	v_mul_f32_e32 v22, v3, v27
	v_fmac_f32_e32 v22, v2, v26
	v_fmac_f32_e32 v22, v31, v28
	v_fmac_f32_e32 v22, v42, v29
	v_mul_f32_e32 v23, 0xbfb8aa3b, v22
	v_exp_f32_e32 v23, v23
	s_nop 0
	v_add_f32_e32 v23, 1.0, v23
	v_rcp_f32_e32 v23, v23
	s_nop 0
	v_mul_f32_e32 v38, v22, v23
	v_mul_f32_e32 v22, v3, v28
	v_fmac_f32_e32 v22, v2, v27
	v_fmac_f32_e32 v22, v31, v29
	v_fmac_f32_e32 v22, v42, v39
	v_mul_f32_e32 v23, 0xbfb8aa3b, v22
	v_exp_f32_e32 v23, v23
	s_nop 0
	v_add_f32_e32 v23, 1.0, v23
	v_rcp_f32_e32 v23, v23
	s_nop 0
	v_mul_f32_e32 v32, v22, v23
	v_mul_f32_e32 v22, v3, v29
	v_fmac_f32_e32 v22, v2, v28
	v_mul_f32_e32 v3, v3, v39
	v_fmac_f32_e32 v22, v31, v39
	v_fmac_f32_e32 v3, v2, v29
	v_fmac_f32_e32 v22, v42, v40
	v_fmac_f32_e32 v3, v31, v40
	v_mul_f32_e32 v23, 0xbfb8aa3b, v22
	v_fmac_f32_e32 v3, v42, v41
	v_exp_f32_e32 v23, v23
	v_mul_f32_e32 v2, 0xbfb8aa3b, v3
	v_exp_f32_e32 v2, v2
	v_add_f32_e32 v23, 1.0, v23
	v_rcp_f32_e32 v23, v23
	v_add_f32_e32 v2, 1.0, v2
	v_rcp_f32_e32 v2, v2
	v_mul_f32_e32 v37, v22, v23
	v_lshl_add_u64 v[22:23], v[0:1], 0, s[14:15]
	s_mov_b32 s14, 0x861c000
	v_mul_f32_e32 v31, v3, v2
	v_add_co_u32_e32 v2, vcc, s14, v0
	s_mov_b64 s[14:15], 0x861c800
	v_lshl_add_u64 v[24:25], v[0:1], 0, s[14:15]
	s_mov_b64 s[14:15], 0x861e000
	v_addc_co_u32_e32 v3, vcc, 0, v1, vcc
	v_lshl_add_u64 v[26:27], v[0:1], 0, s[14:15]
	s_mov_b32 s14, 0x861e000
	v_add_co_u32_e32 v28, vcc, s14, v0
	global_store_dword v[2:3], v39, off offset:-4096
	s_nop 0
	v_addc_co_u32_e32 v29, vcc, 0, v1, vcc
	global_store_dword v[28:29], v41, off
	v_add_co_u32_e32 v28, vcc, s20, v14
	global_store_dword v[2:3], v40, off offset:2048
	s_nop 0
	v_addc_co_u32_e32 v29, vcc, 0, v15, vcc
	global_load_dword v39, v[14:15], off offset:2048
	global_load_dword v42, v[28:29], off
	global_load_dword v43, v[12:13], off offset:2048
	global_load_ushort v44, v[8:9], off offset:1024
	s_mov_b64 s[14:15], 0x400
	v_lshl_add_u64 v[12:13], v[18:19], 0, s[14:15]
	s_movk_i32 s14, 0x5000
	global_load_dword v50, v[10:11], off offset:2048
	v_lshl_add_u64 v[40:41], v[12:13], 0, s[0:1]
	global_load_ushort v45, v[40:41], off
	v_lshl_add_u64 v[40:41], v[12:13], 0, s[2:3]
	global_load_ushort v46, v[40:41], off
	v_lshl_add_u64 v[40:41], v[12:13], 0, s[4:5]
	global_load_ushort v47, v[40:41], off
	v_lshl_add_u64 v[40:41], v[12:13], 0, s[6:7]
	global_load_ushort v48, v[40:41], off
	v_lshl_add_u64 v[40:41], v[12:13], 0, s[8:9]
	global_load_ushort v49, v[40:41], off
	v_lshl_add_u64 v[40:41], v[12:13], 0, s[10:11]
	v_lshl_add_u64 v[12:13], v[12:13], 0, s[12:13]
	global_load_ushort v40, v[40:41], off
	s_nop 0
	global_load_ushort v12, v[12:13], off
	s_waitcnt vmcnt(0)
	v_lshlrev_b32_e32 v44, 16, v44
	v_lshlrev_b32_e32 v45, 16, v45
	v_lshlrev_b32_e32 v46, 16, v46
	v_lshlrev_b32_e32 v47, 16, v47
	v_lshlrev_b32_e32 v48, 16, v48
	v_lshlrev_b32_e32 v49, 16, v49
	v_lshlrev_b32_e32 v40, 16, v40
	v_lshlrev_b32_e32 v41, 16, v12
	v_add_co_u32_e32 v12, vcc, s20, v10
	s_nop 1
	v_addc_co_u32_e32 v13, vcc, 0, v11, vcc
	global_load_dword v51, v[12:13], off
	s_nop 0
	global_load_dword v20, v[20:21], off offset:2048
	v_add_co_u32_e32 v10, vcc, s14, v10
	s_mov_b64 s[14:15], 0x800
	s_nop 0
	v_addc_co_u32_e32 v11, vcc, 0, v11, vcc
	global_load_dword v52, v[10:11], off
	v_add_co_u32_e32 v14, vcc, s24, v14
	s_waitcnt vmcnt(2)
	v_mul_f32_e32 v21, v42, v51
	v_fmac_f32_e32 v21, v39, v50
	s_waitcnt vmcnt(1)
	v_fmac_f32_e32 v21, v43, v20
	v_addc_co_u32_e32 v15, vcc, 0, v15, vcc
	s_waitcnt vmcnt(0)
	v_fmac_f32_e32 v21, v52, v44
	v_mul_f32_e32 v39, 0xbfb8aa3b, v21
	v_exp_f32_e32 v39, v39
	s_nop 0
	v_add_f32_e32 v39, 1.0, v39
	v_rcp_f32_e32 v39, v39
	s_nop 0
	v_mul_f32_e32 v21, v21, v39
	ds_write2st64_b32 v30, v36, v21 offset1:8
	v_mul_f32_e32 v21, v43, v51
	v_fmac_f32_e32 v21, v42, v50
	v_fmac_f32_e32 v21, v20, v44
	v_fmac_f32_e32 v21, v52, v45
	v_mul_f32_e32 v36, 0xbfb8aa3b, v21
	v_exp_f32_e32 v36, v36
	s_nop 0
	v_add_f32_e32 v36, 1.0, v36
	v_rcp_f32_e32 v36, v36
	s_nop 0
	v_mul_f32_e32 v36, v21, v36
	v_mul_f32_e32 v21, v51, v44
	v_fmac_f32_e32 v21, v43, v50
	v_fmac_f32_e32 v21, v20, v45
	v_fmac_f32_e32 v21, v52, v46
	v_mul_f32_e32 v39, 0xbfb8aa3b, v21
	v_exp_f32_e32 v39, v39
	s_nop 0
	v_add_f32_e32 v39, 1.0, v39
	v_rcp_f32_e32 v39, v39
	s_nop 0
	v_mul_f32_e32 v21, v21, v39
	ds_write2st64_b32 v30, v35, v21 offset0:48 offset1:56
	v_mul_f32_e32 v21, v51, v45
	v_fmac_f32_e32 v21, v50, v44
	v_fmac_f32_e32 v21, v20, v46
	v_fmac_f32_e32 v21, v52, v47
	v_mul_f32_e32 v35, 0xbfb8aa3b, v21
	v_exp_f32_e32 v35, v35
	s_nop 0
	v_add_f32_e32 v35, 1.0, v35
	v_rcp_f32_e32 v35, v35
	s_nop 0
	v_mul_f32_e32 v35, v21, v35
	v_mul_f32_e32 v21, v51, v46
	v_fmac_f32_e32 v21, v50, v45
	v_fmac_f32_e32 v21, v20, v47
	v_fmac_f32_e32 v21, v52, v48
	v_mul_f32_e32 v39, 0xbfb8aa3b, v21
	v_exp_f32_e32 v39, v39
	s_nop 0
	v_add_f32_e32 v39, 1.0, v39
	v_rcp_f32_e32 v39, v39
	s_nop 0
	v_mul_f32_e32 v21, v21, v39
	ds_write2st64_b32 v30, v38, v21 offset0:96 offset1:104
	v_mul_f32_e32 v21, v51, v47
	v_fmac_f32_e32 v21, v50, v46
	v_fmac_f32_e32 v21, v20, v48
	v_fmac_f32_e32 v21, v52, v49
	v_mul_f32_e32 v38, 0xbfb8aa3b, v21
	v_exp_f32_e32 v38, v38
	s_nop 0
	v_add_f32_e32 v38, 1.0, v38
	v_rcp_f32_e32 v38, v38
	s_nop 0
	v_mul_f32_e32 v21, v21, v38
	v_mul_f32_e32 v38, v51, v48
	v_fmac_f32_e32 v38, v50, v47
	v_fmac_f32_e32 v38, v20, v49
	v_fmac_f32_e32 v38, v52, v40
	v_mul_f32_e32 v39, 0xbfb8aa3b, v38
	v_exp_f32_e32 v39, v39
	s_nop 0
	v_add_f32_e32 v39, 1.0, v39
	v_rcp_f32_e32 v39, v39
	s_nop 0
	v_mul_f32_e32 v38, v38, v39
	ds_write2st64_b32 v30, v37, v38 offset0:144 offset1:152
	global_store_dword v[22:23], v49, off offset:2048
	global_store_dword v[24:25], v40, off offset:2048
	global_store_dword v[26:27], v41, off offset:2048
	global_load_dword v22, v[16:17], off
	s_nop 0
	global_load_dword v17, v[28:29], off offset:2048
	global_load_dword v16, v[14:15], off
	v_lshl_add_u64 v[14:15], v[18:19], 0, s[14:15]
	v_lshl_add_u64 v[18:19], v[14:15], 0, s[0:1]
	global_load_ushort v8, v[8:9], off offset:2048
	v_lshl_add_u64 v[28:29], v[14:15], 0, s[10:11]
	global_load_ushort v26, v[18:19], off
	v_lshl_add_u64 v[18:19], v[14:15], 0, s[2:3]
	global_load_ushort v25, v[18:19], off
	v_lshl_add_u64 v[18:19], v[14:15], 0, s[4:5]
	global_load_ushort v24, v[18:19], off
	v_lshl_add_u64 v[18:19], v[14:15], 0, s[6:7]
	global_load_ushort v23, v[18:19], off
	v_lshl_add_u64 v[18:19], v[14:15], 0, s[8:9]
	v_lshl_add_u64 v[14:15], v[14:15], 0, s[12:13]
	global_load_ushort v19, v[18:19], off
	global_load_ushort v18, v[28:29], off
	global_load_ushort v9, v[14:15], off
	s_nop 0
	global_load_dword v6, v[6:7], off
	s_nop 0
	global_load_dword v7, v[12:13], off offset:2048
	s_nop 0
	global_load_dword v5, v[4:5], off
	s_nop 0
	global_load_dword v4, v[10:11], off offset:2048
	v_mul_f32_e32 v37, v51, v49
	v_fmac_f32_e32 v37, v50, v48
	v_fmac_f32_e32 v37, v20, v40
	v_fmac_f32_e32 v37, v52, v41
	v_mul_f32_e32 v20, 0xbfb8aa3b, v37
	v_exp_f32_e32 v20, v20
	s_nop 0
	v_add_f32_e32 v20, 1.0, v20
	v_rcp_f32_e32 v20, v20
	s_waitcnt vmcnt(4)
	v_lshlrev_b32_e32 v8, 16, v8
	v_mul_f32_e32 v20, v37, v20
	v_lshlrev_b32_e32 v26, 16, v26
	v_lshlrev_b32_e32 v25, 16, v25
	v_lshlrev_b32_e32 v24, 16, v24
	v_lshlrev_b32_e32 v23, 16, v23
	v_lshlrev_b32_e32 v19, 16, v19
	v_lshlrev_b32_e32 v18, 16, v18
	s_waitcnt vmcnt(2)
	v_mul_f32_e32 v10, v17, v7
	v_fmac_f32_e32 v10, v22, v6
	s_waitcnt vmcnt(1)
	v_fmac_f32_e32 v10, v16, v5
	s_waitcnt vmcnt(0)
	v_fmac_f32_e32 v10, v4, v8
	v_mul_f32_e32 v11, 0xbfb8aa3b, v10
	v_exp_f32_e32 v11, v11
	v_lshlrev_b32_e32 v9, 16, v9
	global_store_dword v[2:3], v19, off
	v_add_co_u32_e32 v2, vcc, 0x861d000, v0
	v_add_f32_e32 v11, 1.0, v11
	v_rcp_f32_e32 v11, v11
	v_addc_co_u32_e32 v3, vcc, 0, v1, vcc
	v_add_co_u32_e32 v0, vcc, 0x861f000, v0
	v_mul_f32_e32 v10, v10, v11
	ds_write2st64_b32 v30, v10, v34 offset0:16 offset1:24
	v_mul_f32_e32 v10, v16, v7
	v_fmac_f32_e32 v10, v17, v6
	v_fmac_f32_e32 v10, v5, v8
	v_fmac_f32_e32 v10, v4, v26
	v_mul_f32_e32 v11, 0xbfb8aa3b, v10
	v_exp_f32_e32 v11, v11
	v_addc_co_u32_e32 v1, vcc, 0, v1, vcc
	v_cmp_gt_i32_e32 vcc, 32, v150
	v_add_f32_e32 v11, 1.0, v11
	v_rcp_f32_e32 v11, v11
	global_store_dword v[2:3], v18, off offset:2048
	global_store_dword v[0:1], v9, off
	v_mul_f32_e32 v10, v10, v11
	ds_write2st64_b32 v30, v36, v10 offset0:32 offset1:40
	v_mul_f32_e32 v10, v7, v8
	v_fmac_f32_e32 v10, v16, v6
	v_fmac_f32_e32 v10, v5, v26
	v_fmac_f32_e32 v10, v4, v25
	v_mul_f32_e32 v11, 0xbfb8aa3b, v10
	v_exp_f32_e32 v11, v11
	s_nop 0
	v_add_f32_e32 v11, 1.0, v11
	v_rcp_f32_e32 v11, v11
	s_nop 0
	v_mul_f32_e32 v10, v10, v11
	ds_write2st64_b32 v30, v10, v33 offset0:64 offset1:72
	v_mul_f32_e32 v10, v7, v26
	v_fmac_f32_e32 v10, v6, v8
	v_fmac_f32_e32 v10, v5, v25
	v_fmac_f32_e32 v10, v4, v24
	v_mul_f32_e32 v8, 0xbfb8aa3b, v10
	v_exp_f32_e32 v8, v8
	s_nop 0
	v_add_f32_e32 v8, 1.0, v8
	v_rcp_f32_e32 v8, v8
	s_nop 0
	v_mul_f32_e32 v8, v10, v8
	ds_write2st64_b32 v30, v35, v8 offset0:80 offset1:88
	v_mul_f32_e32 v8, v7, v25
	v_fmac_f32_e32 v8, v6, v26
	v_fmac_f32_e32 v8, v5, v24
	v_fmac_f32_e32 v8, v4, v23
	v_mul_f32_e32 v10, 0xbfb8aa3b, v8
	v_exp_f32_e32 v10, v10
	s_nop 0
	v_add_f32_e32 v10, 1.0, v10
	v_rcp_f32_e32 v10, v10
	s_nop 0
	v_mul_f32_e32 v8, v8, v10
	ds_write2st64_b32 v30, v8, v32 offset0:112 offset1:120
	v_mul_f32_e32 v8, v7, v24
	v_fmac_f32_e32 v8, v6, v25
	v_fmac_f32_e32 v8, v5, v23
	v_fmac_f32_e32 v8, v4, v19
	v_mul_f32_e32 v10, 0xbfb8aa3b, v8
	v_exp_f32_e32 v10, v10
	s_nop 0
	v_add_f32_e32 v10, 1.0, v10
	v_rcp_f32_e32 v10, v10
	s_nop 0
	v_mul_f32_e32 v8, v8, v10
	ds_write2st64_b32 v30, v21, v8 offset0:128 offset1:136
	v_mul_f32_e32 v8, v7, v23
	v_mul_f32_e32 v7, v7, v19
	v_fmac_f32_e32 v8, v6, v24
	v_fmac_f32_e32 v7, v6, v23
	v_fmac_f32_e32 v8, v5, v19
	v_fmac_f32_e32 v7, v5, v18
	v_fmac_f32_e32 v8, v4, v18
	v_fmac_f32_e32 v7, v4, v9
	v_mul_f32_e32 v10, 0xbfb8aa3b, v8
	v_mul_f32_e32 v4, 0xbfb8aa3b, v7
	v_exp_f32_e32 v10, v10
	v_exp_f32_e32 v4, v4
	v_add_f32_e32 v10, 1.0, v10
	v_add_f32_e32 v4, 1.0, v4
	v_rcp_f32_e32 v10, v10
	v_rcp_f32_e32 v4, v4
	v_mul_f32_e32 v8, v8, v10
	v_mul_f32_e32 v4, v7, v4
	ds_write2st64_b32 v30, v8, v31 offset0:160 offset1:168
	ds_write2st64_b32 v30, v20, v4 offset0:176 offset1:184
	s_and_saveexec_b64 s[0:1], vcc
	s_cbranch_execz .LBB0_741
	v_ashrrev_i32_e32 v0, 2, v150
	v_add_u32_e32 v0, s16, v0
	v_ashrrev_i32_e32 v1, 31, v0
	v_readlane_b32 s2, v254, 55
	v_and_b32_e32 v2, 3, v150
	v_lshlrev_b64 v[0:1], 6, v[0:1]
	v_readlane_b32 s3, v254, 56
	v_lshlrev_b32_e32 v90, 2, v2
	s_load_dwordx4 s[4:7], s[34:35], 0x58
	v_lshl_add_u64 v[0:1], s[2:3], 0, v[0:1]
	v_lshl_add_u64 v[2:3], v[0:1], 0, v[90:91]
	global_load_dword v0, v[2:3], off
	v_lshl_add_u32 v1, v150, 2, v156
	s_mov_b32 s2, 0x41a00000
	s_waitcnt vmcnt(0)
	v_mul_f32_e32 v0, 0xbfb8aa3b, v0
	v_exp_f32_e32 v0, v0
	s_nop 0
	v_add_f32_e32 v0, 1.0, v0
	v_rcp_f32_e32 v0, v0
	ds_write_b32 v1, v0
	s_waitcnt lgkmcnt(0)
	global_load_dword v0, v90, s[4:5]
	global_load_dword v1, v[2:3], off offset:16
	s_nop 0
	global_load_dword v2, v90, s[6:7]
	s_waitcnt vmcnt(0)
	v_add_f32_e32 v1, v1, v2
	v_cmp_nlt_f32_e32 vcc, s2, v1
	s_and_saveexec_b64 s[4:5], vcc
	s_cbranch_execz .LBB0_740
	v_mul_f32_e32 v1, 0x3fb8aa3b, v1
	v_exp_f32_e32 v2, v1
	s_mov_b32 s2, 0x3a83126f
	v_cmp_ngt_f32_e32 vcc, s2, v2
	s_and_saveexec_b64 s[2:3], vcc
	s_xor_b64 s[6:7], exec, s[2:3]
	s_cbranch_execz .LBB0_737
	v_add_f32_e32 v1, 1.0, v2
	s_mov_b32 s2, 0x800000
	v_cmp_gt_f32_e32 vcc, s2, v1
	s_mov_b32 s2, 0x3f317217
	s_nop 0
	v_cndmask_b32_e64 v2, 0, 32, vcc
	v_ldexp_f32 v1, v1, v2
	v_log_f32_e32 v1, v1
	s_nop 0
	v_mul_f32_e32 v2, 0x3f317217, v1
	v_fma_f32 v2, v1, s2, -v2
	v_fmac_f32_e32 v2, 0x3377d1cf, v1
	s_mov_b32 s2, 0x7f800000
	v_fmac_f32_e32 v2, 0x3f317217, v1
	v_cmp_lt_f32_e64 s[2:3], |v1|, s2
	s_nop 1
	v_cndmask_b32_e64 v1, v1, v2, s[2:3]
	v_cndmask_b32_e32 v2, 0, v170, vcc
	v_sub_f32_e32 v1, v1, v2
